# P4 GroupNorm: the two xor-32 ds_bpermute round trips per batch (mean, variance) replaced by copy + v_permlane32_swap; on top of the QK-norm permlane version
# baseline (speedup 1.0000x reference)
.LBB0_548:
	s_or_b32 s58, s88, s87
	v_add_lshl_u32 v96, s58, v168, 6
	s_add_i32 s58, s58, s74
	v_lshl_add_u64 v[0:1], v[98:99], 0, v[96:97]
	s_lshl_b32 s75, s58, 6
	v_mad_u64_u32 v[12:13], s[58:59], v0, s35, v[158:159]
	s_add_u32 s59, s82, s75
	v_mov_b64_e32 v[16:17], s[20:21]
	v_or_b32_e32 v18, s59, v176
	s_addc_u32 s58, s83, 0
	v_or_b32_e32 v68, s59, v118
	s_add_i32 s59, s88, s74
	v_mad_u64_u32 v[16:17], s[88:89], v18, s35, v[16:17]
	v_mad_i32_i24 v17, s58, v196, v17
	v_mov_b32_e32 v117, v97
	v_mad_u64_u32 v[20:21], s[88:89], v68, s35, v[120:121]
	v_lshl_add_u64 v[22:23], v[16:17], 0, s[4:5]
	v_mad_i32_i24 v13, v1, s35, v13
	v_mad_i32_i24 v21, s58, v196, v21
	v_lshl_add_u64 v[24:25], v[22:23], 0, v[116:117]
	global_load_dwordx4 v[0:3], v[12:13], off offset:2096
	global_load_dwordx4 v[4:7], v[12:13], off offset:2080
	global_load_dwordx4 v[8:11], v[12:13], off offset:2064
	s_nop 0
	global_load_dwordx4 v[12:15], v[12:13], off offset:2048
	s_nop 0
	global_load_dwordx4 v[16:19], v[20:21], off
	global_load_dwordx4 v[70:73], v[20:21], off offset:32
	global_load_dwordx4 v[74:77], v[20:21], off offset:64
	global_load_dwordx4 v[64:67], v[20:21], off offset:96
	v_add_co_u32_e32 v26, vcc, s73, v24
	global_load_dwordx4 v[20:23], v[24:25], off offset:1024
	s_nop 0
	v_addc_co_u32_e32 v27, vcc, 0, v25, vcc
	v_lshl_add_u64 v[28:29], v[24:25], 0, s[78:79]
	global_load_dwordx4 v[78:81], v[24:25], off offset:1056
	global_load_dwordx4 v[82:85], v[24:25], off offset:1088
	global_load_dwordx4 v[86:89], v[24:25], off offset:1120
	s_nop 0
	global_load_dwordx4 v[24:27], v[26:27], off offset:1024
	s_nop 0
	global_load_dwordx4 v[90:93], v[28:29], off offset:32
	global_load_dwordx4 v[164:167], v[28:29], off offset:64
	global_load_dwordx4 v[198:201], v[28:29], off offset:96
	s_mulk_i32 s59, 0x2400
	v_add_u32_e32 v69, s59, v181
	s_waitcnt vmcnt(12)
	ds_write_b128 v191, v[12:15]
	ds_write_b128 v191, v[8:11] offset:16
	ds_write_b128 v191, v[4:7] offset:32
	ds_write_b128 v191, v[0:3] offset:48
	s_waitcnt vmcnt(7)
	v_mfma_f32_32x32x16_bf16 v[48:63], v[20:23], v[16:19], 0
	s_waitcnt lgkmcnt(0)
	s_barrier
	ds_read_b128 v[0:3], v69 offset:36864
	ds_read_b128 v[202:205], v69 offset:36896
	ds_read_b128 v[20:23], v69 offset:41472
	ds_read_b128 v[206:209], v69 offset:41504
	s_waitcnt lgkmcnt(3)
	v_mfma_f32_32x32x16_bf16 v[0:15], v[0:3], v[16:19], 0
	s_waitcnt vmcnt(3)
	v_mfma_f32_32x32x16_bf16 v[32:47], v[24:27], v[16:19], 0
	v_mfma_f32_32x32x16_bf16 v[48:63], v[78:81], v[70:73], v[48:63]
	s_waitcnt lgkmcnt(1)
	v_mfma_f32_32x32x16_bf16 v[16:31], v[20:23], v[16:19], 0
	v_mfma_f32_32x32x16_bf16 v[0:15], v[202:205], v[70:73], v[0:15]
	s_waitcnt vmcnt(2)
	v_mfma_f32_32x32x16_bf16 v[32:47], v[90:93], v[70:73], v[32:47]
	v_mfma_f32_32x32x16_bf16 v[48:63], v[82:85], v[74:77], v[48:63]
	s_waitcnt lgkmcnt(0)
	v_mfma_f32_32x32x16_bf16 v[16:31], v[206:209], v[70:73], v[16:31]
	ds_read_b128 v[70:73], v69 offset:36928
	ds_read_b128 v[78:81], v69 offset:36960
	s_waitcnt lgkmcnt(1)
	v_mfma_f32_32x32x16_bf16 v[0:15], v[70:73], v[74:77], v[0:15]
	ds_read_b128 v[70:73], v69 offset:41536
	ds_read_b128 v[82:85], v69 offset:41568
	v_mov_b32_e32 v69, s58
	s_waitcnt vmcnt(1)
	v_mfma_f32_32x32x16_bf16 v[32:47], v[164:167], v[74:77], v[32:47]
	v_mad_u64_u32 v[166:167], s[88:89], v68, s35, v[160:161]
	v_lshlrev_b64 v[68:69], 11, v[68:69]
	v_lshl_add_u64 v[164:165], v[162:163], 0, v[68:69]
	ds_read_b64_tr_b16 v[68:69], v197
	v_mad_i32_i24 v167, s58, v196, v167
	s_mov_b32 s88, 4
	v_mfma_f32_32x32x16_bf16 v[48:63], v[86:89], v[64:67], v[48:63]
	s_waitcnt lgkmcnt(2)
	v_mfma_f32_32x32x16_bf16 v[16:31], v[70:73], v[74:77], v[16:31]
	s_nop 9
	v_mul_f32_e64 v48, v124, v48
	v_mul_f32_e64 v49, v125, v49
	v_mul_f32_e64 v50, v128, v50
	v_mul_f32_e64 v51, v129, v51
	v_mul_f32_e64 v52, v132, v52
	v_mul_f32_e64 v53, v133, v53
	v_pk_mul_f32 v[54:55], v[136:137], v[54:55]
	v_cvt_pk_bf16_f32 v48, v48, v49
	v_cvt_pk_bf16_f32 v49, v50, v51
	v_cvt_pk_bf16_f32 v50, v52, v53
	v_cvt_pk_bf16_f32 v51, v54, v55
	s_waitcnt vmcnt(0)
	v_mfma_f32_32x32x16_bf16 v[32:47], v[198:201], v[64:67], v[32:47]
	ds_read_b64_tr_b16 v[70:71], v197 offset:1152
	ds_read_b64_tr_b16 v[74:75], v197 offset:1216
	ds_read_b64_tr_b16 v[72:73], v197 offset:64
	ds_read_b64_tr_b16 v[198:199], v197 offset:2304
	ds_read_b64_tr_b16 v[200:201], v197 offset:3456
	ds_read_b64_tr_b16 v[204:205], v197 offset:3520
	ds_read_b64_tr_b16 v[202:203], v197 offset:2368
	v_pk_mul_f32 v[52:53], v[140:141], v[56:57]
	v_pk_mul_f32 v[54:55], v[152:153], v[62:63]
	ds_read_b64_tr_b16 v[206:207], v197 offset:4608
	ds_read_b64_tr_b16 v[208:209], v197 offset:5760
	ds_read_b64_tr_b16 v[212:213], v197 offset:5824
	ds_read_b64_tr_b16 v[210:211], v197 offset:4672
	ds_read_b64_tr_b16 v[214:215], v197 offset:6912
	ds_read_b64_tr_b16 v[216:217], v197 offset:8064
	v_pk_mul_f32 v[32:33], v[126:127], v[32:33]
	v_mfma_f32_32x32x16_bf16 v[0:15], v[78:81], v[64:67], v[0:15]
	v_mul_f32_e64 v36, v134, v36
	v_mul_f32_e64 v37, v135, v37
	v_mul_f32_e64 v38, v138, v38
	v_mul_f32_e64 v39, v139, v39
	v_cvt_pk_bf16_f32 v36, v36, v37
	v_cvt_pk_bf16_f32 v37, v38, v39
	v_pk_mul_f32 v[38:39], v[142:143], v[40:41]
	v_pk_mul_f32 v[40:41], v[146:147], v[42:43]
	v_pk_mul_f32 v[42:43], v[150:151], v[44:45]
	s_waitcnt lgkmcnt(14)
	v_mfma_f32_32x32x16_bf16 v[16:31], v[82:85], v[64:67], v[16:31]
	v_mul_f32_e64 v44, v154, v46
	v_mul_f32_e64 v45, v155, v47
	v_mov_b32_e32 v46, v4
	v_mul_f32_e32 v4, v122, v6
	v_mul_f32_e32 v12, v122, v12
	s_waitcnt lgkmcnt(12)
	v_mfma_f32_32x32x16_bf16 v[80:95], v[68:71], v[48:51], 0
	s_nop 4
	v_mul_f32_e32 v6, v122, v22
	v_mov_b32_e32 v22, v7
	v_mov_b32_e32 v47, v20
	v_mul_f32_e32 v20, v122, v9
	s_waitcnt lgkmcnt(10)
	v_mfma_f32_32x32x16_bf16 v[64:79], v[72:75], v[48:51], 0
	v_mul_f32_e64 v48, v144, v58
	v_mul_f32_e64 v49, v145, v59
	v_mul_f32_e64 v50, v148, v60
	v_mul_f32_e64 v51, v149, v61
	v_cvt_pk_bf16_f32 v58, v52, v53
	v_cvt_pk_bf16_f32 v59, v48, v49
	v_cvt_pk_bf16_f32 v60, v50, v51
	v_cvt_pk_bf16_f32 v61, v54, v55
	s_waitcnt lgkmcnt(8)
	s_nop 0
	v_mfma_f32_32x32x16_bf16 v[80:95], v[198:201], v[58:61], v[80:95]
	ds_read_b64_tr_b16 v[200:201], v197 offset:8128
	ds_read_b64_tr_b16 v[198:199], v197 offset:6976
	global_load_dwordx4 v[48:51], v[156:157], off
	global_load_dwordx2 v[56:57], v[166:167], off offset:3072
	global_load_dwordx2 v[54:55], v[166:167], off offset:3088
	global_load_dwordx2 v[52:53], v[166:167], off offset:3104
	s_waitcnt lgkmcnt(8)
	v_mfma_f32_32x32x16_bf16 v[64:79], v[202:205], v[58:61], v[64:79]
	v_mul_f32_e64 v58, v130, v34
	v_mul_f32_e64 v59, v131, v35
	v_cvt_pk_bf16_f32 v34, v32, v33
	v_cvt_pk_bf16_f32 v35, v58, v59
	global_load_dwordx2 v[32:33], v[166:167], off offset:3120
	global_load_dwordx4 v[224:227], v[156:157], off offset:32
	global_load_dwordx4 v[228:231], v[156:157], off offset:64
	global_load_dwordx4 v[232:235], v[156:157], off offset:96
	global_load_dwordx4 v[236:239], v[156:157], off offset:128
	global_load_dwordx4 v[240:243], v[156:157], off offset:160
	global_load_dwordx4 v[244:247], v[156:157], off offset:192
	global_load_dwordx4 v[248:251], v[156:157], off offset:224
	s_waitcnt lgkmcnt(6)
	v_mfma_f32_32x32x16_bf16 v[80:95], v[206:209], v[34:37], v[80:95]
	s_waitcnt lgkmcnt(4)
	v_mfma_f32_32x32x16_bf16 v[64:79], v[210:213], v[34:37], v[64:79]
	v_cvt_pk_bf16_f32 v34, v38, v39
	v_cvt_pk_bf16_f32 v35, v40, v41
	v_cvt_pk_bf16_f32 v36, v42, v43
	v_cvt_pk_bf16_f32 v37, v44, v45
	v_mul_f32_e32 v38, v122, v25
	v_mul_f32_e32 v40, v122, v28
	v_mov_b32_e32 v28, v13
	s_waitcnt lgkmcnt(2)
	v_mfma_f32_32x32x16_bf16 v[80:95], v[214:217], v[34:37], v[80:95]
	v_mul_f32_e32 v42, v122, v15
	v_mul_f32_e32 v44, v122, v31
	s_waitcnt lgkmcnt(0)
	v_mfma_f32_32x32x16_bf16 v[64:79], v[198:201], v[34:37], v[64:79]
	global_load_dwordx2 v[206:207], v[166:167], off offset:3136
	global_load_dwordx2 v[208:209], v[166:167], off offset:3152
	global_load_dwordx2 v[210:211], v[166:167], off offset:3168
	global_load_dwordx2 v[212:213], v[166:167], off offset:3184
	s_nop 7
	v_mov_b32_e32 v36, v87
	v_fma_f32 v0, v122, v0, v80
	v_fma_f32 v1, v123, v1, v81
	v_mov_b32_e32 v34, v84
	v_fma_f32 v9, v122, v5, v85
	v_pk_fma_f32 v[2:3], v[122:123], v[2:3], v[82:83]
	v_mov_b32_e32 v87, v9
	v_fma_f32 v15, v122, v8, v88
	v_mov_b32_e32 v37, v71
	v_pk_fma_f32 v[16:17], v[122:123], v[16:17], v[64:65]
	v_pk_fma_f32 v[22:23], v[122:123], v[22:23], v[36:37]
	v_pk_add_f32 v[36:37], v[0:1], v[16:17]
	v_mov_b32_e32 v35, v68
	v_fma_f32 v5, v122, v21, v69
	v_fma_f32 v21, v122, v24, v72
	v_mov_b32_e32 v24, v93
	v_mov_b32_e32 v25, v77
	v_pk_fma_f32 v[18:19], v[122:123], v[18:19], v[66:67]
	v_add_f32_e32 v7, 0, v36
	v_pk_fma_f32 v[34:35], v[122:123], v[46:47], v[34:35]
	v_pk_fma_f32 v[24:25], v[122:123], v[28:29], v[24:25]
	v_pk_add_f32 v[28:29], v[2:3], v[18:19]
	v_add_f32_e32 v7, v37, v7
	v_pk_add_f32 v[62:63], v[34:35], v[34:35] op_sel_hi:[0,1]
	v_add_f32_e32 v7, v28, v7
	v_mov_b32_e32 v71, v63
	v_add_f32_e32 v7, v29, v7
	v_pk_add_f32 v[68:69], v[86:87], v[4:5]
	v_mov_b32_e32 v8, v34
	v_mov_b32_e32 v4, v35
	v_fma_f32 v31, v122, v14, v94
	v_mov_b32_e32 v14, v89
	v_fma_f32 v43, v122, v30, v78
	v_mov_b32_e32 v30, v95
	v_pk_add_f32 v[46:47], v[14:15], v[20:21]
	v_mov_b32_e32 v20, v21
	v_pk_add_f32 v[64:65], v[22:23], v[22:23] op_sel_hi:[0,1]
	v_pk_add_f32 v[58:59], v[30:31], v[42:43]
	v_mov_b32_e32 v64, v73
	v_pk_fma_f32 v[10:11], v[122:123], v[10:11], v[90:91]
	s_waitcnt vmcnt(14)
	v_lshlrev_b32_e32 v28, 16, v57
	v_and_b32_e32 v29, 0xffff0000, v57
	v_lshlrev_b32_e32 v34, 16, v56
	v_and_b32_e32 v35, 0xffff0000, v56
	v_pk_add_f32 v[56:57], v[70:71], v[6:7]
	v_mul_f32_e32 v21, 0xbfb8aa3b, v34
	v_pk_add_f32 v[6:7], v[68:69], v[56:57]
	v_mul_f32_e32 v39, 0xbfb8aa3b, v28
	v_mul_f32_e32 v41, 0xbfb8aa3b, v29
	v_pk_add_f32 v[6:7], v[6:7], v[6:7] op_sel_hi:[0,1]
	v_exp_f32_e32 v42, v21
	v_exp_f32_e32 v45, v39
	v_exp_f32_e32 v41, v41
	v_mov_b32_e32 v39, v7
	v_pk_add_f32 v[6:7], v[64:65], v[38:39]
	v_pk_fma_f32 v[26:27], v[122:123], v[26:27], v[74:75]
	v_mov_b32_e32 v69, v22
	v_mov_b32_e32 v57, v23
	v_pk_add_f32 v[22:23], v[46:47], v[6:7]
	v_pk_add_f32 v[60:61], v[10:11], v[26:27]
	v_mov_b32_e32 v21, v6
	v_pk_add_f32 v[6:7], v[22:23], v[22:23] op_sel_hi:[0,1]
	v_mov_b32_e32 v93, v11
	v_mov_b32_e32 v13, v27
	v_mov_b32_e32 v77, v60
	v_add_f32_e32 v38, 1.0, v42
	v_add_f32_e32 v6, 1.0, v45
	v_add_f32_e32 v39, 1.0, v41
	v_mov_b32_e32 v41, v7
	v_pk_add_f32 v[12:13], v[92:93], v[12:13]
	v_rcp_f32_e32 v22, v38
	v_rcp_f32_e32 v38, v6
	v_pk_add_f32 v[6:7], v[76:77], v[40:41]
	v_mov_b32_e32 v37, v12
	v_pk_add_f32 v[12:13], v[12:13], v[6:7]
	v_pk_add_f32 v[66:67], v[24:25], v[24:25] op_sel_hi:[0,1]
	v_mov_b32_e32 v36, v24
	v_pk_mov_b32 v[24:25], v[24:25], v[6:7] op_sel:[1,0]
	v_pk_add_f32 v[6:7], v[12:13], v[12:13] op_sel_hi:[0,1]
	v_mov_b32_e32 v66, v79
	v_mov_b32_e32 v45, v7
	v_pk_add_f32 v[12:13], v[66:67], v[44:45]
	v_mul_f32_e32 v30, 0xbfb8aa3b, v35
	v_pk_add_f32 v[6:7], v[58:59], v[12:13]
	v_exp_f32_e32 v30, v30
	v_add_f32_e32 v6, v6, v7
	v_mov_b32_e32 v7, v6
	s_nop 1
	v_permlane32_swap_b32_e32 v7, v6
	v_mov_b32_e32 v14, v15
	v_add_f32_e32 v30, 1.0, v30
	v_rcp_f32_e32 v23, v30
	v_mov_b32_e32 v15, v46
	s_waitcnt lgkmcnt(0)
	v_add_f32_e32 v6, v6, v7
	v_mul_f32_e32 v30, 0x3c800000, v6
	v_mov_b32_e32 v59, v31
	v_pk_add_f32 v[16:17], v[16:17], v[30:31] op_sel_hi:[1,0] neg_lo:[0,1] neg_hi:[0,1]
	v_mov_b32_e32 v13, v43
	v_pk_add_f32 v[40:41], v[0:1], v[30:31] op_sel_hi:[1,0] neg_lo:[0,1] neg_hi:[0,1]
	v_pk_add_f32 v[44:45], v[10:11], v[30:31] op_sel_hi:[1,0] neg_lo:[0,1] neg_hi:[0,1]
	v_pk_add_f32 v[0:1], v[24:25], v[30:31] op_sel_hi:[1,0] neg_lo:[0,1] neg_hi:[0,1]
	v_pk_add_f32 v[24:25], v[58:59], v[30:31] op_sel_hi:[1,0] neg_lo:[0,1] neg_hi:[0,1]
	v_pk_add_f32 v[58:59], v[14:15], v[30:31] op_sel_hi:[1,0] neg_lo:[0,1] neg_hi:[0,1]
	v_pk_add_f32 v[14:15], v[18:19], v[30:31] op_sel_hi:[1,0] neg_lo:[0,1] neg_hi:[0,1]
	v_pk_add_f32 v[10:11], v[56:57], v[30:31] op_sel_hi:[1,0] neg_lo:[0,1] neg_hi:[0,1]
	v_pk_mul_f32 v[56:57], v[16:17], v[16:17]
	v_pk_add_f32 v[42:43], v[2:3], v[30:31] op_sel_hi:[1,0] neg_lo:[0,1] neg_hi:[0,1]
	v_pk_add_f32 v[6:7], v[26:27], v[30:31] op_sel_hi:[1,0] neg_lo:[0,1] neg_hi:[0,1]
	v_pk_add_f32 v[26:27], v[36:37], v[30:31] op_sel_hi:[1,0] neg_lo:[0,1] neg_hi:[0,1]
	v_pk_add_f32 v[2:3], v[12:13], v[30:31] op_sel_hi:[1,0] neg_lo:[0,1] neg_hi:[0,1]
	v_pk_add_f32 v[36:37], v[68:69], v[30:31] op_sel_hi:[1,0] neg_lo:[0,1] neg_hi:[0,1]
	v_pk_add_f32 v[46:47], v[8:9], v[30:31] op_sel_hi:[1,0] neg_lo:[0,1] neg_hi:[0,1]
	v_pk_add_f32 v[12:13], v[4:5], v[30:31] op_sel_hi:[1,0] neg_lo:[0,1] neg_hi:[0,1]
	v_pk_add_f32 v[8:9], v[20:21], v[30:31] op_sel_hi:[1,0] neg_lo:[0,1] neg_hi:[0,1]
	v_pk_mul_f32 v[30:31], v[14:15], v[14:15]
	v_pk_fma_f32 v[56:57], v[40:41], v[40:41], v[56:57]
	v_pk_fma_f32 v[30:31], v[42:43], v[42:43], v[30:31]
	v_add_f32_e32 v56, v56, v57
	v_pk_mul_f32 v[62:63], v[12:13], v[12:13]
	v_add_f32_e32 v30, v30, v56
	v_pk_fma_f32 v[62:63], v[46:47], v[46:47], v[62:63]
	v_add_f32_e32 v30, v31, v30
	v_pk_mul_f32 v[60:61], v[10:11], v[10:11]
	v_add_f32_e32 v30, v62, v30
	v_pk_fma_f32 v[60:61], v[36:37], v[36:37], v[60:61]
	v_add_f32_e32 v30, v63, v30
	v_pk_mul_f32 v[64:65], v[8:9], v[8:9]
	v_add_f32_e32 v30, v60, v30
	v_pk_fma_f32 v[64:65], v[58:59], v[58:59], v[64:65]
	v_add_f32_e32 v30, v61, v30
	v_pk_mul_f32 v[4:5], v[6:7], v[6:7]
	v_add_f32_e32 v30, v64, v30
	v_pk_fma_f32 v[4:5], v[44:45], v[44:45], v[4:5]
	v_add_f32_e32 v30, v65, v30
	v_pk_mul_f32 v[18:19], v[0:1], v[0:1]
	v_add_f32_e32 v4, v4, v30
	v_pk_fma_f32 v[18:19], v[26:27], v[26:27], v[18:19]
	v_add_f32_e32 v4, v5, v4
	v_pk_mul_f32 v[20:21], v[2:3], v[2:3]
	v_add_f32_e32 v4, v19, v4
	v_pk_fma_f32 v[20:21], v[24:25], v[24:25], v[20:21]
	v_add_f32_e32 v4, v18, v4
	v_add_f32_e32 v4, v21, v4
	v_add_f32_e32 v4, v20, v4
	v_mov_b32_e32 v5, v4
	s_nop 1
	v_permlane32_swap_b32_e32 v5, v4
	v_rcp_f32_e32 v39, v39
	s_waitcnt lgkmcnt(0)
	v_add_f32_e32 v4, v4, v5
	v_fmamk_f32 v4, v4, 0x3c800000, v192
	v_mul_f32_e32 v5, 0x4b800000, v4
	v_cmp_gt_f32_e32 vcc, s27, v4
	s_nop 1
	v_cndmask_b32_e32 v4, v4, v5, vcc
	v_rsq_f32_e32 v4, v4
	s_nop 0
	v_mul_f32_e32 v5, 0x45800000, v4
	v_cndmask_b32_e32 v4, v4, v5, vcc
	v_pk_mul_f32 v[18:19], v[40:41], v[4:5] op_sel_hi:[1,0]
	v_pk_mul_f32 v[20:21], v[42:43], v[4:5] op_sel_hi:[1,0]
	v_pk_mul_f32 v[18:19], v[48:49], v[18:19]
	v_pk_mul_f32 v[20:21], v[50:51], v[20:21]
	v_pk_mul_f32 v[18:19], v[18:19], v[34:35]
	v_pk_mul_f32 v[20:21], v[20:21], v[28:29]
	v_pk_mul_f32 v[18:19], v[22:23], v[18:19]
	v_pk_mul_f32 v[20:21], v[38:39], v[20:21]
	v_cvt_pk_bf16_f32 v18, v18, v19
	v_cvt_pk_bf16_f32 v19, v20, v21
	global_store_dwordx2 v[164:165], v[18:19], off
	s_waitcnt vmcnt(14)
	v_lshlrev_b32_e32 v22, 16, v55
	v_and_b32_e32 v23, 0xffff0000, v55
	v_lshlrev_b32_e32 v28, 16, v54
	v_and_b32_e32 v29, 0xffff0000, v54
	v_mul_f32_e32 v5, 0xbfb8aa3b, v28
	v_mul_f32_e32 v30, 0xbfb8aa3b, v29
	v_mul_f32_e32 v31, 0xbfb8aa3b, v22
	v_mul_f32_e32 v34, 0xbfb8aa3b, v23
	v_exp_f32_e32 v5, v5
	v_exp_f32_e32 v30, v30
	v_exp_f32_e32 v31, v31
	v_exp_f32_e32 v34, v34
	v_add_f32_e32 v5, 1.0, v5
	v_add_f32_e32 v35, 1.0, v30
	v_add_f32_e32 v38, 1.0, v31
	v_add_f32_e32 v39, 1.0, v34
	v_rcp_f32_e32 v30, v5
	v_rcp_f32_e32 v31, v35
	v_rcp_f32_e32 v34, v38
	v_rcp_f32_e32 v35, v39
	v_pk_mul_f32 v[38:39], v[46:47], v[4:5] op_sel_hi:[1,0]
	v_pk_mul_f32 v[36:37], v[36:37], v[4:5] op_sel_hi:[1,0]
	s_and_b64 vcc, exec, s[84:85]
	s_mov_b64 s[84:85], 0
	s_waitcnt vmcnt(11)
	v_pk_mul_f32 v[18:19], v[224:225], v[38:39]
	v_pk_mul_f32 v[20:21], v[226:227], v[36:37]
	v_pk_mul_f32 v[18:19], v[18:19], v[28:29]
	v_pk_mul_f32 v[20:21], v[20:21], v[22:23]
	v_pk_mul_f32 v[18:19], v[30:31], v[18:19]
	v_pk_mul_f32 v[20:21], v[34:35], v[20:21]
	v_cvt_pk_bf16_f32 v18, v18, v19
	v_cvt_pk_bf16_f32 v19, v20, v21
	global_store_dwordx2 v[164:165], v[18:19], off offset:16
	v_lshlrev_b32_e32 v22, 16, v52
	v_and_b32_e32 v23, 0xffff0000, v52
	v_lshlrev_b32_e32 v28, 16, v53
	v_and_b32_e32 v29, 0xffff0000, v53
	v_mul_f32_e32 v5, 0xbfb8aa3b, v22
	v_mul_f32_e32 v30, 0xbfb8aa3b, v23
	v_mul_f32_e32 v31, 0xbfb8aa3b, v28
	v_mul_f32_e32 v34, 0xbfb8aa3b, v29
	v_exp_f32_e32 v5, v5
	v_exp_f32_e32 v30, v30
	v_exp_f32_e32 v31, v31
	v_exp_f32_e32 v34, v34
	v_add_f32_e32 v5, 1.0, v5
	v_add_f32_e32 v35, 1.0, v30
	v_add_f32_e32 v36, 1.0, v31
	v_add_f32_e32 v37, 1.0, v34
	v_rcp_f32_e32 v30, v5
	v_rcp_f32_e32 v31, v35
	v_rcp_f32_e32 v34, v36
	v_rcp_f32_e32 v35, v37
	v_pk_mul_f32 v[36:37], v[58:59], v[4:5] op_sel_hi:[1,0]
	v_pk_mul_f32 v[38:39], v[44:45], v[4:5] op_sel_hi:[1,0]
	s_waitcnt vmcnt(11)
	v_pk_mul_f32 v[18:19], v[228:229], v[36:37]
	v_pk_mul_f32 v[20:21], v[230:231], v[38:39]
	v_pk_mul_f32 v[18:19], v[18:19], v[22:23]
	v_pk_mul_f32 v[20:21], v[20:21], v[28:29]
	v_pk_mul_f32 v[18:19], v[30:31], v[18:19]
	v_pk_mul_f32 v[20:21], v[34:35], v[20:21]
	v_cvt_pk_bf16_f32 v18, v18, v19
	v_cvt_pk_bf16_f32 v19, v20, v21
	global_store_dwordx2 v[164:165], v[18:19], off offset:32
	v_lshlrev_b32_e32 v28, 16, v32
	v_and_b32_e32 v29, 0xffff0000, v32
	v_lshlrev_b32_e32 v30, 16, v33
	v_and_b32_e32 v31, 0xffff0000, v33
	v_mul_f32_e32 v5, 0xbfb8aa3b, v28
	v_mul_f32_e32 v32, 0xbfb8aa3b, v29
	v_mul_f32_e32 v33, 0xbfb8aa3b, v30
	v_mul_f32_e32 v34, 0xbfb8aa3b, v31
	v_exp_f32_e32 v5, v5
	v_exp_f32_e32 v32, v32
	v_exp_f32_e32 v33, v33
	v_exp_f32_e32 v34, v34
	v_add_f32_e32 v5, 1.0, v5
	v_add_f32_e32 v35, 1.0, v32
	v_add_f32_e32 v36, 1.0, v33
	v_add_f32_e32 v37, 1.0, v34
	v_rcp_f32_e32 v32, v5
	v_rcp_f32_e32 v33, v35
	v_rcp_f32_e32 v34, v36
	v_rcp_f32_e32 v35, v37
	v_pk_mul_f32 v[26:27], v[26:27], v[4:5] op_sel_hi:[1,0]
	v_pk_mul_f32 v[24:25], v[24:25], v[4:5] op_sel_hi:[1,0]
	s_waitcnt vmcnt(11)
	v_pk_mul_f32 v[18:19], v[232:233], v[26:27] op_sel:[0,1] op_sel_hi:[1,0]
	v_pk_mul_f32 v[20:21], v[234:235], v[24:25] op_sel:[0,1] op_sel_hi:[1,0]
	v_pk_mul_f32 v[18:19], v[18:19], v[28:29]
	v_pk_mul_f32 v[20:21], v[20:21], v[30:31]
	v_pk_mul_f32 v[18:19], v[32:33], v[18:19]
	v_pk_mul_f32 v[20:21], v[34:35], v[20:21]
	v_cvt_pk_bf16_f32 v18, v18, v19
	v_cvt_pk_bf16_f32 v19, v20, v21
	global_store_dwordx2 v[164:165], v[18:19], off offset:48
	s_waitcnt vmcnt(7)
	v_lshlrev_b32_e32 v30, 16, v207
	v_and_b32_e32 v31, 0xffff0000, v207
	v_lshlrev_b32_e32 v32, 16, v206
	v_and_b32_e32 v33, 0xffff0000, v206
	v_mul_f32_e32 v5, 0xbfb8aa3b, v32
	v_mul_f32_e32 v22, 0xbfb8aa3b, v33
	v_mul_f32_e32 v23, 0xbfb8aa3b, v30
	v_mul_f32_e32 v34, 0xbfb8aa3b, v31
	v_exp_f32_e32 v5, v5
	v_exp_f32_e32 v22, v22
	v_exp_f32_e32 v23, v23
	v_exp_f32_e32 v34, v34
	v_add_f32_e32 v5, 1.0, v5
	v_add_f32_e32 v35, 1.0, v22
	v_add_f32_e32 v36, 1.0, v23
	v_add_f32_e32 v37, 1.0, v34
	v_rcp_f32_e32 v22, v5
	v_rcp_f32_e32 v23, v35
	v_rcp_f32_e32 v34, v36
	v_rcp_f32_e32 v35, v37
	v_pk_mul_f32 v[16:17], v[16:17], v[4:5] op_sel_hi:[1,0]
	v_pk_mul_f32 v[14:15], v[14:15], v[4:5] op_sel_hi:[1,0]
	v_pk_mul_f32 v[16:17], v[236:237], v[16:17]
	v_pk_mul_f32 v[14:15], v[238:239], v[14:15]
	v_pk_mul_f32 v[16:17], v[16:17], v[32:33]
	v_pk_mul_f32 v[14:15], v[14:15], v[30:31]
	v_pk_mul_f32 v[16:17], v[22:23], v[16:17]
	v_pk_mul_f32 v[14:15], v[34:35], v[14:15]
	v_cvt_pk_bf16_f32 v16, v16, v17
	v_cvt_pk_bf16_f32 v17, v14, v15
	global_store_dwordx2 v[164:165], v[16:17], off offset:64
	s_waitcnt vmcnt(7)
	v_lshlrev_b32_e32 v18, 16, v209
	v_and_b32_e32 v19, 0xffff0000, v209
	v_lshlrev_b32_e32 v20, 16, v208
	v_and_b32_e32 v21, 0xffff0000, v208
	v_mul_f32_e32 v5, 0xbfb8aa3b, v20
	v_mul_f32_e32 v22, 0xbfb8aa3b, v21
	v_mul_f32_e32 v23, 0xbfb8aa3b, v18
	v_mul_f32_e32 v24, 0xbfb8aa3b, v19
	v_exp_f32_e32 v5, v5
	v_exp_f32_e32 v22, v22
	v_exp_f32_e32 v23, v23
	v_exp_f32_e32 v24, v24
	v_add_f32_e32 v5, 1.0, v5
	v_add_f32_e32 v25, 1.0, v22
	v_add_f32_e32 v30, 1.0, v23
	v_add_f32_e32 v31, 1.0, v24
	v_rcp_f32_e32 v22, v5
	v_rcp_f32_e32 v23, v25
	v_rcp_f32_e32 v24, v30
	v_rcp_f32_e32 v25, v31
	v_pk_mul_f32 v[12:13], v[12:13], v[4:5] op_sel_hi:[1,0]
	v_pk_mul_f32 v[10:11], v[10:11], v[4:5] op_sel_hi:[1,0]
	v_pk_mul_f32 v[12:13], v[240:241], v[12:13]
	v_pk_mul_f32 v[10:11], v[242:243], v[10:11]
	v_pk_mul_f32 v[12:13], v[12:13], v[20:21]
	v_pk_mul_f32 v[10:11], v[10:11], v[18:19]
	v_pk_mul_f32 v[12:13], v[22:23], v[12:13]
	v_pk_mul_f32 v[10:11], v[24:25], v[10:11]
	v_cvt_pk_bf16_f32 v12, v12, v13
	v_cvt_pk_bf16_f32 v13, v10, v11
	global_store_dwordx2 v[164:165], v[12:13], off offset:80
	s_waitcnt vmcnt(7)
	v_lshlrev_b32_e32 v14, 16, v210
	v_and_b32_e32 v15, 0xffff0000, v210
	v_lshlrev_b32_e32 v16, 16, v211
	v_and_b32_e32 v17, 0xffff0000, v211
	v_mul_f32_e32 v5, 0xbfb8aa3b, v14
	v_mul_f32_e32 v18, 0xbfb8aa3b, v15
	v_mul_f32_e32 v19, 0xbfb8aa3b, v16
	v_mul_f32_e32 v20, 0xbfb8aa3b, v17
	v_exp_f32_e32 v5, v5
	v_exp_f32_e32 v18, v18
	v_exp_f32_e32 v19, v19
	v_exp_f32_e32 v20, v20
	v_add_f32_e32 v5, 1.0, v5
	v_add_f32_e32 v21, 1.0, v18
	v_add_f32_e32 v22, 1.0, v19
	v_add_f32_e32 v23, 1.0, v20
	v_rcp_f32_e32 v18, v5
	v_rcp_f32_e32 v19, v21
	v_rcp_f32_e32 v20, v22
	v_rcp_f32_e32 v21, v23
	v_pk_mul_f32 v[8:9], v[8:9], v[4:5] op_sel_hi:[1,0]
	v_pk_mul_f32 v[6:7], v[6:7], v[4:5] op_sel_hi:[1,0]
	v_pk_mul_f32 v[8:9], v[244:245], v[8:9]
	v_pk_mul_f32 v[6:7], v[246:247], v[6:7]
	v_pk_mul_f32 v[8:9], v[8:9], v[14:15]
	v_pk_mul_f32 v[6:7], v[6:7], v[16:17]
	v_pk_mul_f32 v[8:9], v[18:19], v[8:9]
	v_pk_mul_f32 v[6:7], v[20:21], v[6:7]
	v_cvt_pk_bf16_f32 v8, v8, v9
	v_cvt_pk_bf16_f32 v9, v6, v7
	global_store_dwordx2 v[164:165], v[8:9], off offset:96
	s_waitcnt vmcnt(7)
	v_lshlrev_b32_e32 v10, 16, v212
	v_and_b32_e32 v11, 0xffff0000, v212
	v_lshlrev_b32_e32 v12, 16, v213
	v_and_b32_e32 v13, 0xffff0000, v213
	v_mul_f32_e32 v5, 0xbfb8aa3b, v10
	v_mul_f32_e32 v14, 0xbfb8aa3b, v11
	v_mul_f32_e32 v15, 0xbfb8aa3b, v12
	v_mul_f32_e32 v16, 0xbfb8aa3b, v13
	v_exp_f32_e32 v5, v5
	v_exp_f32_e32 v14, v14
	v_exp_f32_e32 v15, v15
	v_exp_f32_e32 v16, v16
	v_add_f32_e32 v5, 1.0, v5
	v_add_f32_e32 v17, 1.0, v14
	v_add_f32_e32 v18, 1.0, v15
	v_add_f32_e32 v19, 1.0, v16
	v_rcp_f32_e32 v14, v5
	v_rcp_f32_e32 v15, v17
	v_rcp_f32_e32 v16, v18
	v_rcp_f32_e32 v17, v19
	v_pk_mul_f32 v[0:1], v[0:1], v[4:5] op_sel_hi:[1,0]
	v_pk_mul_f32 v[2:3], v[2:3], v[4:5] op_sel_hi:[1,0]
	v_pk_mul_f32 v[0:1], v[248:249], v[0:1] op_sel:[0,1] op_sel_hi:[1,0]
	v_pk_mul_f32 v[2:3], v[250:251], v[2:3] op_sel:[0,1] op_sel_hi:[1,0]
	v_pk_mul_f32 v[0:1], v[0:1], v[10:11]
	v_pk_mul_f32 v[2:3], v[2:3], v[12:13]
	v_pk_mul_f32 v[0:1], v[14:15], v[0:1]
	v_pk_mul_f32 v[2:3], v[16:17], v[2:3]
	v_cvt_pk_bf16_f32 v0, v0, v1
	v_cvt_pk_bf16_f32 v1, v2, v3
	global_store_dwordx2 v[164:165], v[0:1], off offset:112
	s_barrier
	s_cbranch_vccnz .LBB0_548
	s_add_i32 s86, s86, s26
	s_cmpk_gt_i32 s86, 0xff
	s_cbranch_scc0 .LBB0_540
	s_branch .LBB0_551
